# S5 pass 2: C-projection state-row LDS reads issued 4-at-once with counted waits; redundant LDS wait before next-chunk staging removed (on top of pass-1 rewrite + prologue batching)
# baseline (speedup 1.0000x reference)
.LBB0_873:
	v_cndmask_b32_e64 v93, v83, 0, s[10:11]
	v_cndmask_b32_e64 v92, v82, 0, s[10:11]
	v_cndmask_b32_e64 v91, v81, 0, s[10:11]
	v_cndmask_b32_e64 v90, v80, 0, s[10:11]
	v_add_u32_e32 v81, v139, v141
	v_add_u32_e32 v83, v139, v142
	v_mfma_f32_16x16x32_bf16 v[94:97], v[90:93], v[0:3], 0
	v_add_u32_e32 v88, v139, v143
	v_add_u32_e32 v82, s86, v140
	v_mul_f32_e32 v80, v132, v87
	v_mfma_f32_16x16x32_bf16 v[98:101], v[90:93], v[4:7], 0
	v_mul_f32_e32 v87, v128, v87
	v_fma_f32 v80, v128, v86, -v80
	v_fmac_f32_e32 v87, v132, v86
	v_mfma_f32_16x16x32_bf16 v[102:105], v[90:93], v[8:11], 0
	ds_write_b128 v81, v[94:97]
	s_nop 2
	ds_write_b128 v81, v[98:101] offset:1280
	s_nop 2
	ds_write_b128 v81, v[102:105] offset:2560
	v_cndmask_b32_e64 v79, v79, 0, s[10:11]
	v_mfma_f32_16x16x32_bf16 v[106:109], v[90:93], v[12:15], 0
	v_cndmask_b32_e64 v78, v78, 0, s[10:11]
	v_cndmask_b32_e64 v77, v77, 0, s[10:11]
	v_cndmask_b32_e64 v76, v76, 0, s[10:11]
	v_mfma_f32_16x16x32_bf16 v[94:97], v[90:93], v[20:23], 0
	v_cndmask_b32_e64 v75, v75, 0, s[10:11]
	v_cndmask_b32_e64 v74, v74, 0, s[10:11]
	v_cndmask_b32_e64 v73, v73, 0, s[10:11]
	v_mfma_f32_16x16x32_bf16 v[110:113], v[90:93], v[16:19], 0
	ds_write_b128 v83, v[106:109]
	s_nop 6
	ds_write_b128 v81, v[110:113] offset:5120
	v_mfma_f32_16x16x32_bf16 v[98:101], v[90:93], v[24:27], 0
	ds_write_b128 v81, v[94:97] offset:6400
	s_nop 6
	ds_write_b128 v81, v[98:101] offset:7680
	v_mfma_f32_16x16x32_bf16 v[94:97], v[90:93], v[28:31], 0
	v_cndmask_b32_e64 v72, v72, 0, s[10:11]
	v_cndmask_b32_e64 v71, v71, 0, s[10:11]
	v_cndmask_b32_e64 v70, v70, 0, s[10:11]
	v_mfma_f32_16x16x32_bf16 v[90:93], v[90:93], v[48:51], 0
	v_cndmask_b32_e64 v69, v69, 0, s[10:11]
	s_nop 2
	ds_write_b128 v88, v[94:97]
	s_waitcnt lgkmcnt(0)
	ds_read_b128 v[94:97], v82
	ds_read_b128 v[98:101], v82 offset:16
	ds_read_b128 v[102:105], v82 offset:32
	ds_read_b128 v[106:109], v82 offset:48
	ds_read_b128 v[110:113], v82 offset:5120
	ds_read_b128 v[170:173], v82 offset:5136
	ds_read_b128 v[174:177], v82 offset:5152
	ds_read_b128 v[178:181], v82 offset:5168
	s_waitcnt lgkmcnt(7)
	v_add_f32_e32 v80, v80, v94
	s_waitcnt lgkmcnt(3)
	v_add_f32_e32 v86, v87, v110
	v_cvt_pk_bf16_f32 v87, v80, v86
	ds_write_b32 v149, v87 offset:10240
	v_mul_f32_e32 v87, v132, v86
	v_mul_f32_e32 v86, v128, v86
	v_fma_f32 v87, v128, v80, -v87
	v_fmac_f32_e32 v86, v132, v80
	v_add_f32_e32 v87, v95, v87
	v_add_f32_e32 v80, v111, v86
	v_cvt_pk_bf16_f32 v86, v87, v80
	ds_write_b32 v149, v86 offset:10512
	v_mul_f32_e32 v86, v132, v80
	v_mul_f32_e32 v80, v128, v80
	v_fma_f32 v86, v128, v87, -v86
	v_fmac_f32_e32 v80, v132, v87
	v_add_f32_e32 v86, v96, v86
	v_add_f32_e32 v80, v112, v80
	v_cvt_pk_bf16_f32 v87, v86, v80
	ds_write_b32 v149, v87 offset:10784
	v_mul_f32_e32 v87, v132, v80
	v_mul_f32_e32 v80, v128, v80
	v_fma_f32 v87, v128, v86, -v87
	v_fmac_f32_e32 v80, v132, v86
	v_add_f32_e32 v87, v97, v87
	v_add_f32_e32 v80, v113, v80
	v_cvt_pk_bf16_f32 v86, v87, v80
	ds_write_b32 v149, v86 offset:11056
	v_mul_f32_e32 v86, v132, v80
	v_mul_f32_e32 v80, v128, v80
	v_fma_f32 v86, v128, v87, -v86
	v_fmac_f32_e32 v80, v132, v87
	v_add_f32_e32 v86, v98, v86
	s_waitcnt lgkmcnt(6)
	v_add_f32_e32 v80, v170, v80
	v_cvt_pk_bf16_f32 v87, v86, v80
	ds_write_b32 v149, v87 offset:11328
	v_mul_f32_e32 v87, v132, v80
	v_mul_f32_e32 v80, v128, v80
	v_fma_f32 v87, v128, v86, -v87
	v_fmac_f32_e32 v80, v132, v86
	v_add_f32_e32 v87, v99, v87
	v_add_f32_e32 v80, v171, v80
	v_cvt_pk_bf16_f32 v86, v87, v80
	ds_write_b32 v149, v86 offset:11600
	v_mul_f32_e32 v86, v132, v80
	v_mul_f32_e32 v80, v128, v80
	v_fma_f32 v86, v128, v87, -v86
	v_fmac_f32_e32 v80, v132, v87
	v_add_f32_e32 v86, v100, v86
	v_add_f32_e32 v80, v172, v80
	v_cvt_pk_bf16_f32 v87, v86, v80
	ds_write_b32 v149, v87 offset:11872
	v_mul_f32_e32 v87, v132, v80
	v_mul_f32_e32 v80, v128, v80
	v_fma_f32 v87, v128, v86, -v87
	v_fmac_f32_e32 v80, v132, v86
	v_add_f32_e32 v87, v101, v87
	v_add_f32_e32 v80, v173, v80
	v_cvt_pk_bf16_f32 v86, v87, v80
	ds_write_b32 v149, v86 offset:12144
	v_mul_f32_e32 v86, v132, v80
	v_mul_f32_e32 v80, v128, v80
	v_fma_f32 v86, v128, v87, -v86
	v_fmac_f32_e32 v80, v132, v87
	v_add_f32_e32 v86, v102, v86
	s_waitcnt lgkmcnt(9)
	v_add_f32_e32 v80, v174, v80
	v_cvt_pk_bf16_f32 v87, v86, v80
	ds_write_b32 v149, v87 offset:12416
	v_mul_f32_e32 v87, v132, v80
	v_mul_f32_e32 v80, v128, v80
	v_fma_f32 v87, v128, v86, -v87
	v_fmac_f32_e32 v80, v132, v86
	v_add_f32_e32 v87, v103, v87
	v_add_f32_e32 v80, v175, v80
	v_cvt_pk_bf16_f32 v86, v87, v80
	ds_write_b32 v149, v86 offset:12688
	v_mul_f32_e32 v86, v132, v80
	v_mul_f32_e32 v80, v128, v80
	v_fma_f32 v86, v128, v87, -v86
	v_fmac_f32_e32 v80, v132, v87
	v_add_f32_e32 v86, v104, v86
	v_add_f32_e32 v80, v176, v80
	v_cvt_pk_bf16_f32 v87, v86, v80
	ds_write_b32 v149, v87 offset:12960
	v_mul_f32_e32 v87, v132, v80
	v_mul_f32_e32 v80, v128, v80
	v_fma_f32 v87, v128, v86, -v87
	v_fmac_f32_e32 v80, v132, v86
	v_add_f32_e32 v87, v105, v87
	v_add_f32_e32 v80, v177, v80
	v_cvt_pk_bf16_f32 v86, v87, v80
	ds_write_b32 v149, v86 offset:13232
	v_mul_f32_e32 v86, v132, v80
	v_mul_f32_e32 v80, v128, v80
	v_fma_f32 v86, v128, v87, -v86
	v_fmac_f32_e32 v80, v132, v87
	v_add_f32_e32 v86, v106, v86
	s_waitcnt lgkmcnt(12)
	v_add_f32_e32 v80, v178, v80
	v_cvt_pk_bf16_f32 v87, v86, v80
	ds_write_b32 v149, v87 offset:13504
	v_mul_f32_e32 v87, v132, v80
	v_mul_f32_e32 v80, v128, v80
	v_fma_f32 v87, v128, v86, -v87
	v_fmac_f32_e32 v80, v132, v86
	v_add_f32_e32 v87, v107, v87
	v_add_f32_e32 v80, v179, v80
	v_cvt_pk_bf16_f32 v86, v87, v80
	ds_write_b32 v149, v86 offset:13776
	v_mul_f32_e32 v86, v132, v80
	v_mul_f32_e32 v80, v128, v80
	v_fma_f32 v86, v128, v87, -v86
	v_fmac_f32_e32 v80, v132, v87
	v_add_f32_e32 v86, v108, v86
	v_add_f32_e32 v80, v180, v80
	v_cvt_pk_bf16_f32 v87, v86, v80
	ds_write_b32 v149, v87 offset:14048
	v_mul_f32_e32 v87, v132, v80
	v_mul_f32_e32 v80, v128, v80
	v_fma_f32 v87, v128, v86, -v87
	v_fmac_f32_e32 v80, v132, v86
	v_add_f32_e32 v87, v109, v87
	v_add_f32_e32 v86, v181, v80
	v_cvt_pk_bf16_f32 v80, v87, v86
	ds_write_b32 v149, v80 offset:14320
	s_waitcnt lgkmcnt(0)
	v_add_u32_e32 v80, v150, v138
	ds_read_b128 v[94:97], v80 offset:10240
	ds_read_b128 v[98:101], v80 offset:10304
	ds_read_b128 v[184:187], v80 offset:10368
	ds_read_b128 v[188:191], v80 offset:10432
	s_waitcnt lgkmcnt(3)
	v_mfma_f32_16x16x32_bf16 v[90:93], v[94:97], v[32:35], v[90:93]
	v_cndmask_b32_e64 v68, v68, 0, s[10:11]
	s_add_u32 s30, s30, 0x40000
	s_waitcnt lgkmcnt(2)
	v_mfma_f32_16x16x32_bf16 v[90:93], v[98:101], v[36:39], v[90:93]
	s_addc_u32 s31, s31, 0
	s_cmp_eq_u32 s30, 0x240000
	s_waitcnt lgkmcnt(1)
	v_mfma_f32_16x16x32_bf16 v[90:93], v[184:187], v[40:43], v[90:93]
	s_cselect_b64 s[34:35], -1, 0
	s_waitcnt lgkmcnt(0)
	v_mfma_f32_16x16x32_bf16 v[90:93], v[188:191], v[44:47], v[90:93]
	v_mfma_f32_16x16x32_bf16 v[98:101], v[76:79], v[4:7], 0
	v_mfma_f32_16x16x32_bf16 v[102:105], v[76:79], v[8:11], 0
	s_nop 5
	v_mul_f32_e32 v89, 0x3d122279, v90
	v_fmaak_f32 v89, v90, v89, 0x3f4c422a
	v_mul_f32_e32 v89, v90, v89
	v_add_f32_e32 v89, v89, v89
	v_mul_f32_e32 v89, 0xbfb8aa3b, v89
	v_exp_f32_e32 v89, v89
	v_mul_f32_e32 v94, 0x3d122279, v91
	v_fmaak_f32 v94, v91, v94, 0x3f4c422a
	v_mul_f32_e32 v94, v91, v94
	v_add_f32_e32 v94, v94, v94
	v_mul_f32_e32 v94, 0xbfb8aa3b, v94
	v_add_f32_e32 v89, 1.0, v89
	v_exp_f32_e32 v94, v94
	v_rcp_f32_e32 v89, v89
	v_mfma_f32_16x16x32_bf16 v[106:109], v[76:79], v[12:15], 0
	v_add_f32_e32 v94, 1.0, v94
	v_mul_f32_e32 v89, v90, v89
	v_mul_f32_e32 v90, 0x3d122279, v92
	v_rcp_f32_e32 v94, v94
	v_fmaak_f32 v90, v92, v90, 0x3f4c422a
	v_mul_f32_e32 v90, v92, v90
	v_add_f32_e32 v90, v90, v90
	v_cvt_pk_bf16_f32 v89, v89, v89
	v_mul_f32_e32 v90, 0xbfb8aa3b, v90
	ds_write_b16 v160, v89 offset:14592
	v_mul_f32_e32 v89, v91, v94
	v_exp_f32_e32 v90, v90
	v_mul_f32_e32 v91, 0x3d122279, v93
	v_fmaak_f32 v91, v93, v91, 0x3f4c422a
	v_mul_f32_e32 v91, v93, v91
	v_add_f32_e32 v91, v91, v91
	v_add_f32_e32 v90, 1.0, v90
	v_mul_f32_e32 v91, 0xbfb8aa3b, v91
	v_rcp_f32_e32 v90, v90
	v_exp_f32_e32 v91, v91
	v_cvt_pk_bf16_f32 v89, v89, v89
	ds_write_b16 v160, v89 offset:14624
	v_mul_f32_e32 v89, v92, v90
	v_add_f32_e32 v90, 1.0, v91
	v_rcp_f32_e32 v90, v90
	v_mfma_f32_16x16x32_bf16 v[94:97], v[76:79], v[0:3], 0
	v_cvt_pk_bf16_f32 v89, v89, v89
	ds_write_b16 v160, v89 offset:14656
	v_mul_f32_e32 v89, v93, v90
	v_cvt_pk_bf16_f32 v89, v89, v89
	v_mfma_f32_16x16x32_bf16 v[90:93], v[76:79], v[16:19], 0
	ds_write_b16 v161, v89 offset:14592
	s_nop 0
	s_nop 3
	ds_write_b128 v81, v[94:97]
	v_mfma_f32_16x16x32_bf16 v[94:97], v[76:79], v[20:23], 0
	ds_write_b128 v81, v[98:101] offset:1280
	ds_write_b128 v81, v[102:105] offset:2560
	ds_write_b128 v83, v[106:109]
	v_mul_f32_e32 v89, v132, v86
	v_mul_f32_e32 v86, v128, v86
	v_mfma_f32_16x16x32_bf16 v[98:101], v[76:79], v[24:27], 0
	ds_write_b128 v81, v[90:93] offset:5120
	s_nop 0
	ds_write_b128 v81, v[94:97] offset:6400
	s_nop 4
	ds_write_b128 v81, v[98:101] offset:7680
	v_fma_f32 v89, v128, v87, -v89
	v_mfma_f32_16x16x32_bf16 v[90:93], v[76:79], v[28:31], 0
	v_fmac_f32_e32 v86, v132, v87
	v_mfma_f32_16x16x32_bf16 v[76:79], v[76:79], v[48:51], 0
	s_nop 5
	ds_write_b128 v88, v[90:93]
	s_waitcnt lgkmcnt(0)
	ds_read_b128 v[90:93], v82
	ds_read_b128 v[94:97], v82 offset:16
	ds_read_b128 v[98:101], v82 offset:32
	ds_read_b128 v[102:105], v82 offset:48
	ds_read_b128 v[106:109], v82 offset:5120
	ds_read_b128 v[110:113], v82 offset:5136
	ds_read_b128 v[170:173], v82 offset:5152
	ds_read_b128 v[174:177], v82 offset:5168
	s_waitcnt lgkmcnt(7)
	v_add_f32_e32 v89, v89, v90
	s_waitcnt lgkmcnt(3)
	v_add_f32_e32 v86, v86, v106
	v_cvt_pk_bf16_f32 v87, v89, v86
	ds_write_b32 v149, v87 offset:10240
	v_mul_f32_e32 v87, v132, v86
	v_mul_f32_e32 v86, v128, v86
	v_fma_f32 v87, v128, v89, -v87
	v_fmac_f32_e32 v86, v132, v89
	v_add_f32_e32 v87, v91, v87
	v_add_f32_e32 v86, v107, v86
	v_cvt_pk_bf16_f32 v89, v87, v86
	ds_write_b32 v149, v89 offset:10512
	v_mul_f32_e32 v89, v132, v86
	v_mul_f32_e32 v86, v128, v86
	v_fma_f32 v89, v128, v87, -v89
	v_fmac_f32_e32 v86, v132, v87
	v_add_f32_e32 v89, v92, v89
	v_add_f32_e32 v86, v108, v86
	v_cvt_pk_bf16_f32 v87, v89, v86
	ds_write_b32 v149, v87 offset:10784
	v_mul_f32_e32 v87, v132, v86
	v_mul_f32_e32 v86, v128, v86
	v_fma_f32 v87, v128, v89, -v87
	v_fmac_f32_e32 v86, v132, v89
	v_add_f32_e32 v87, v93, v87
	v_add_f32_e32 v86, v109, v86
	v_cvt_pk_bf16_f32 v89, v87, v86
	ds_write_b32 v149, v89 offset:11056
	v_mul_f32_e32 v89, v132, v86
	v_mul_f32_e32 v86, v128, v86
	v_fma_f32 v89, v128, v87, -v89
	v_fmac_f32_e32 v86, v132, v87
	v_add_f32_e32 v89, v94, v89
	s_waitcnt lgkmcnt(6)
	v_add_f32_e32 v86, v110, v86
	v_cvt_pk_bf16_f32 v87, v89, v86
	ds_write_b32 v149, v87 offset:11328
	v_mul_f32_e32 v87, v132, v86
	v_mul_f32_e32 v86, v128, v86
	v_fma_f32 v87, v128, v89, -v87
	v_fmac_f32_e32 v86, v132, v89
	v_add_f32_e32 v87, v95, v87
	v_add_f32_e32 v86, v111, v86
	v_cvt_pk_bf16_f32 v89, v87, v86
	ds_write_b32 v149, v89 offset:11600
	v_mul_f32_e32 v89, v132, v86
	v_mul_f32_e32 v86, v128, v86
	v_fma_f32 v89, v128, v87, -v89
	v_fmac_f32_e32 v86, v132, v87
	v_add_f32_e32 v89, v96, v89
	v_add_f32_e32 v86, v112, v86
	v_cvt_pk_bf16_f32 v87, v89, v86
	ds_write_b32 v149, v87 offset:11872
	v_mul_f32_e32 v87, v132, v86
	v_mul_f32_e32 v86, v128, v86
	v_fma_f32 v87, v128, v89, -v87
	v_fmac_f32_e32 v86, v132, v89
	v_add_f32_e32 v87, v97, v87
	v_add_f32_e32 v86, v113, v86
	v_cvt_pk_bf16_f32 v89, v87, v86
	ds_write_b32 v149, v89 offset:12144
	v_mul_f32_e32 v89, v132, v86
	v_mul_f32_e32 v86, v128, v86
	v_fma_f32 v89, v128, v87, -v89
	v_fmac_f32_e32 v86, v132, v87
	v_add_f32_e32 v89, v98, v89
	s_waitcnt lgkmcnt(9)
	v_add_f32_e32 v86, v170, v86
	v_cvt_pk_bf16_f32 v87, v89, v86
	ds_write_b32 v149, v87 offset:12416
	v_mul_f32_e32 v87, v132, v86
	v_mul_f32_e32 v86, v128, v86
	v_fma_f32 v87, v128, v89, -v87
	v_fmac_f32_e32 v86, v132, v89
	v_add_f32_e32 v87, v99, v87
	v_add_f32_e32 v86, v171, v86
	v_cvt_pk_bf16_f32 v89, v87, v86
	ds_write_b32 v149, v89 offset:12688
	v_mul_f32_e32 v89, v132, v86
	v_mul_f32_e32 v86, v128, v86
	v_fma_f32 v89, v128, v87, -v89
	v_fmac_f32_e32 v86, v132, v87
	v_add_f32_e32 v89, v100, v89
	v_add_f32_e32 v86, v172, v86
	v_cvt_pk_bf16_f32 v87, v89, v86
	ds_write_b32 v149, v87 offset:12960
	v_mul_f32_e32 v87, v132, v86
	v_mul_f32_e32 v86, v128, v86
	v_fma_f32 v87, v128, v89, -v87
	v_fmac_f32_e32 v86, v132, v89
	v_add_f32_e32 v87, v101, v87
	v_add_f32_e32 v86, v173, v86
	v_cvt_pk_bf16_f32 v89, v87, v86
	ds_write_b32 v149, v89 offset:13232
	v_mul_f32_e32 v89, v132, v86
	v_mul_f32_e32 v86, v128, v86
	v_fma_f32 v89, v128, v87, -v89
	v_fmac_f32_e32 v86, v132, v87
	v_add_f32_e32 v89, v102, v89
	s_waitcnt lgkmcnt(12)
	v_add_f32_e32 v86, v174, v86
	v_cvt_pk_bf16_f32 v87, v89, v86
	ds_write_b32 v149, v87 offset:13504
	v_mul_f32_e32 v87, v132, v86
	v_mul_f32_e32 v86, v128, v86
	v_fma_f32 v87, v128, v89, -v87
	v_fmac_f32_e32 v86, v132, v89
	v_add_f32_e32 v87, v103, v87
	v_add_f32_e32 v86, v175, v86
	v_cvt_pk_bf16_f32 v89, v87, v86
	ds_write_b32 v149, v89 offset:13776
	v_mul_f32_e32 v89, v132, v86
	v_mul_f32_e32 v86, v128, v86
	v_fma_f32 v89, v128, v87, -v89
	v_fmac_f32_e32 v86, v132, v87
	v_add_f32_e32 v89, v104, v89
	v_add_f32_e32 v86, v176, v86
	v_cvt_pk_bf16_f32 v87, v89, v86
	ds_write_b32 v149, v87 offset:14048
	v_mul_f32_e32 v87, v132, v86
	v_mul_f32_e32 v86, v128, v86
	v_fma_f32 v87, v128, v89, -v87
	v_fmac_f32_e32 v86, v132, v89
	v_add_f32_e32 v87, v105, v87
	v_add_f32_e32 v86, v177, v86
	v_cvt_pk_bf16_f32 v89, v87, v86
	ds_write_b32 v149, v89 offset:14320
	s_waitcnt lgkmcnt(0)
	ds_read_b128 v[90:93], v80 offset:10240
	ds_read_b128 v[94:97], v80 offset:10304
	ds_read_b128 v[184:187], v80 offset:10368
	ds_read_b128 v[188:191], v80 offset:10432
	s_waitcnt lgkmcnt(3)
	v_mfma_f32_16x16x32_bf16 v[76:79], v[90:93], v[32:35], v[76:79]
	s_waitcnt lgkmcnt(2)
	v_mfma_f32_16x16x32_bf16 v[76:79], v[94:97], v[36:39], v[76:79]
	s_waitcnt lgkmcnt(1)
	v_mfma_f32_16x16x32_bf16 v[76:79], v[184:187], v[40:43], v[76:79]
	s_waitcnt lgkmcnt(0)
	v_mfma_f32_16x16x32_bf16 v[76:79], v[188:191], v[44:47], v[76:79]
	v_mfma_f32_16x16x32_bf16 v[94:97], v[72:75], v[4:7], 0
	v_mfma_f32_16x16x32_bf16 v[98:101], v[72:75], v[8:11], 0
	s_nop 5
	v_mul_f32_e32 v89, 0x3d122279, v76
	v_fmaak_f32 v89, v76, v89, 0x3f4c422a
	v_mul_f32_e32 v89, v76, v89
	v_mul_f32_e32 v90, 0x3d122279, v77
	v_add_f32_e32 v89, v89, v89
	v_fmaak_f32 v90, v77, v90, 0x3f4c422a
	v_mul_f32_e32 v89, 0xbfb8aa3b, v89
	v_mul_f32_e32 v90, v77, v90
	v_exp_f32_e32 v89, v89
	v_add_f32_e32 v90, v90, v90
	v_mul_f32_e32 v90, 0xbfb8aa3b, v90
	v_exp_f32_e32 v90, v90
	v_add_f32_e32 v89, 1.0, v89
	v_rcp_f32_e32 v89, v89
	v_mfma_f32_16x16x32_bf16 v[102:105], v[72:75], v[12:15], 0
	v_add_f32_e32 v90, 1.0, v90
	v_rcp_f32_e32 v90, v90
	v_mul_f32_e32 v76, v76, v89
	v_cvt_pk_bf16_f32 v76, v76, v76
	ds_write_b16 v160, v76 offset:15104
	v_mul_f32_e32 v76, v77, v90
	v_mul_f32_e32 v77, 0x3d122279, v78
	v_fmaak_f32 v77, v78, v77, 0x3f4c422a
	v_mul_f32_e32 v77, v78, v77
	v_add_f32_e32 v77, v77, v77
	v_mul_f32_e32 v77, 0xbfb8aa3b, v77
	v_exp_f32_e32 v77, v77
	v_mul_f32_e32 v89, 0x3d122279, v79
	v_fmaak_f32 v89, v79, v89, 0x3f4c422a
	v_mul_f32_e32 v89, v79, v89
	v_add_f32_e32 v89, v89, v89
	v_add_f32_e32 v77, 1.0, v77
	v_mul_f32_e32 v89, 0xbfb8aa3b, v89
	v_rcp_f32_e32 v77, v77
	v_exp_f32_e32 v89, v89
	v_cvt_pk_bf16_f32 v76, v76, v76
	ds_write_b16 v160, v76 offset:15136
	v_mul_f32_e32 v76, v78, v77
	v_add_f32_e32 v77, 1.0, v89
	v_rcp_f32_e32 v77, v77
	v_mfma_f32_16x16x32_bf16 v[90:93], v[72:75], v[0:3], 0
	v_cvt_pk_bf16_f32 v76, v76, v76
	ds_write_b16 v160, v76 offset:15168
	v_mul_f32_e32 v76, v79, v77
	v_cvt_pk_bf16_f32 v89, v76, v76
	v_mfma_f32_16x16x32_bf16 v[76:79], v[72:75], v[16:19], 0
	ds_write_b16 v162, v89 offset:14592
	s_nop 0
	s_nop 3
	ds_write_b128 v81, v[90:93]
	v_mfma_f32_16x16x32_bf16 v[90:93], v[72:75], v[20:23], 0
	ds_write_b128 v81, v[94:97] offset:1280
	ds_write_b128 v81, v[98:101] offset:2560
	ds_write_b128 v83, v[102:105]
	v_mul_f32_e32 v89, v132, v86
	v_mul_f32_e32 v86, v128, v86
	v_mfma_f32_16x16x32_bf16 v[94:97], v[72:75], v[24:27], 0
	ds_write_b128 v81, v[76:79] offset:5120
	s_nop 0
	ds_write_b128 v81, v[90:93] offset:6400
	s_nop 4
	ds_write_b128 v81, v[94:97] offset:7680
	v_fma_f32 v89, v128, v87, -v89
	v_mfma_f32_16x16x32_bf16 v[76:79], v[72:75], v[28:31], 0
	v_fmac_f32_e32 v86, v132, v87
	v_mfma_f32_16x16x32_bf16 v[72:75], v[72:75], v[48:51], 0
	s_nop 5
	ds_write_b128 v88, v[76:79]
	s_waitcnt lgkmcnt(0)
	ds_read_b128 v[76:79], v82
	ds_read_b128 v[90:93], v82 offset:16
	ds_read_b128 v[94:97], v82 offset:32
	ds_read_b128 v[98:101], v82 offset:48
	ds_read_b128 v[102:105], v82 offset:5120
	ds_read_b128 v[106:109], v82 offset:5136
	ds_read_b128 v[110:113], v82 offset:5152
	ds_read_b128 v[170:173], v82 offset:5168
	s_waitcnt lgkmcnt(7)
	v_add_f32_e32 v76, v89, v76
	s_waitcnt lgkmcnt(3)
	v_add_f32_e32 v86, v86, v102
	v_cvt_pk_bf16_f32 v87, v76, v86
	ds_write_b32 v149, v87 offset:10240
	v_mul_f32_e32 v87, v132, v86
	v_mul_f32_e32 v86, v128, v86
	v_fma_f32 v87, v128, v76, -v87
	v_fmac_f32_e32 v86, v132, v76
	v_add_f32_e32 v77, v77, v87
	v_add_f32_e32 v76, v103, v86
	v_cvt_pk_bf16_f32 v86, v77, v76
	ds_write_b32 v149, v86 offset:10512
	v_mul_f32_e32 v86, v132, v76
	v_mul_f32_e32 v76, v128, v76
	v_fma_f32 v86, v128, v77, -v86
	v_fmac_f32_e32 v76, v132, v77
	v_add_f32_e32 v78, v78, v86
	v_add_f32_e32 v76, v104, v76
	v_cvt_pk_bf16_f32 v77, v78, v76
	ds_write_b32 v149, v77 offset:10784
	v_mul_f32_e32 v77, v132, v76
	v_mul_f32_e32 v76, v128, v76
	v_fma_f32 v77, v128, v78, -v77
	v_fmac_f32_e32 v76, v132, v78
	v_add_f32_e32 v77, v79, v77
	v_add_f32_e32 v76, v105, v76
	v_cvt_pk_bf16_f32 v78, v77, v76
	ds_write_b32 v149, v78 offset:11056
	v_mul_f32_e32 v78, v132, v76
	v_mul_f32_e32 v76, v128, v76
	v_fma_f32 v78, v128, v77, -v78
	v_fmac_f32_e32 v76, v132, v77
	v_add_f32_e32 v78, v90, v78
	s_waitcnt lgkmcnt(6)
	v_add_f32_e32 v76, v106, v76
	v_cvt_pk_bf16_f32 v77, v78, v76
	ds_write_b32 v149, v77 offset:11328
	v_mul_f32_e32 v77, v132, v76
	v_mul_f32_e32 v76, v128, v76
	v_fma_f32 v77, v128, v78, -v77
	v_fmac_f32_e32 v76, v132, v78
	v_add_f32_e32 v77, v91, v77
	v_add_f32_e32 v76, v107, v76
	v_cvt_pk_bf16_f32 v78, v77, v76
	ds_write_b32 v149, v78 offset:11600
	v_mul_f32_e32 v78, v132, v76
	v_mul_f32_e32 v76, v128, v76
	v_fma_f32 v78, v128, v77, -v78
	v_fmac_f32_e32 v76, v132, v77
	v_add_f32_e32 v78, v92, v78
	v_add_f32_e32 v76, v108, v76
	v_cvt_pk_bf16_f32 v77, v78, v76
	ds_write_b32 v149, v77 offset:11872
	v_mul_f32_e32 v77, v132, v76
	v_mul_f32_e32 v76, v128, v76
	v_fma_f32 v77, v128, v78, -v77
	v_fmac_f32_e32 v76, v132, v78
	v_add_f32_e32 v77, v93, v77
	v_add_f32_e32 v76, v109, v76
	v_cvt_pk_bf16_f32 v78, v77, v76
	ds_write_b32 v149, v78 offset:12144
	v_mul_f32_e32 v78, v132, v76
	v_mul_f32_e32 v76, v128, v76
	v_fma_f32 v78, v128, v77, -v78
	v_fmac_f32_e32 v76, v132, v77
	v_add_f32_e32 v78, v94, v78
	s_waitcnt lgkmcnt(9)
	v_add_f32_e32 v76, v110, v76
	v_cvt_pk_bf16_f32 v77, v78, v76
	ds_write_b32 v149, v77 offset:12416
	v_mul_f32_e32 v77, v132, v76
	v_mul_f32_e32 v76, v128, v76
	v_fma_f32 v77, v128, v78, -v77
	v_fmac_f32_e32 v76, v132, v78
	v_add_f32_e32 v77, v95, v77
	v_add_f32_e32 v76, v111, v76
	v_cvt_pk_bf16_f32 v78, v77, v76
	ds_write_b32 v149, v78 offset:12688
	v_mul_f32_e32 v78, v132, v76
	v_mul_f32_e32 v76, v128, v76
	v_fma_f32 v78, v128, v77, -v78
	v_fmac_f32_e32 v76, v132, v77
	v_add_f32_e32 v78, v96, v78
	v_add_f32_e32 v76, v112, v76
	v_cvt_pk_bf16_f32 v77, v78, v76
	ds_write_b32 v149, v77 offset:12960
	v_mul_f32_e32 v77, v132, v76
	v_mul_f32_e32 v76, v128, v76
	v_fma_f32 v77, v128, v78, -v77
	v_fmac_f32_e32 v76, v132, v78
	v_add_f32_e32 v77, v97, v77
	v_add_f32_e32 v76, v113, v76
	v_cvt_pk_bf16_f32 v78, v77, v76
	ds_write_b32 v149, v78 offset:13232
	v_mul_f32_e32 v78, v132, v76
	v_mul_f32_e32 v76, v128, v76
	v_fma_f32 v78, v128, v77, -v78
	v_fmac_f32_e32 v76, v132, v77
	v_add_f32_e32 v78, v98, v78
	s_waitcnt lgkmcnt(12)
	v_add_f32_e32 v76, v170, v76
	v_cvt_pk_bf16_f32 v77, v78, v76
	ds_write_b32 v149, v77 offset:13504
	v_mul_f32_e32 v77, v132, v76
	v_mul_f32_e32 v76, v128, v76
	v_fma_f32 v77, v128, v78, -v77
	v_fmac_f32_e32 v76, v132, v78
	v_add_f32_e32 v77, v99, v77
	v_add_f32_e32 v76, v171, v76
	v_cvt_pk_bf16_f32 v78, v77, v76
	ds_write_b32 v149, v78 offset:13776
	v_mul_f32_e32 v78, v132, v76
	v_mul_f32_e32 v76, v128, v76
	v_fma_f32 v78, v128, v77, -v78
	v_fmac_f32_e32 v76, v132, v77
	v_add_f32_e32 v78, v100, v78
	v_add_f32_e32 v76, v172, v76
	v_cvt_pk_bf16_f32 v77, v78, v76
	ds_write_b32 v149, v77 offset:14048
	v_mul_f32_e32 v77, v132, v76
	v_mul_f32_e32 v76, v128, v76
	v_fma_f32 v77, v128, v78, -v77
	v_fmac_f32_e32 v76, v132, v78
	v_add_f32_e32 v110, v101, v77
	v_add_f32_e32 v111, v173, v76
	v_cvt_pk_bf16_f32 v76, v110, v111
	ds_write_b32 v149, v76 offset:14320
	s_waitcnt lgkmcnt(0)
	ds_read_b128 v[76:79], v80 offset:10240
	ds_read_b128 v[90:93], v80 offset:10304
	ds_read_b128 v[184:187], v80 offset:10368
	ds_read_b128 v[188:191], v80 offset:10432
	s_waitcnt lgkmcnt(3)
	v_mfma_f32_16x16x32_bf16 v[72:75], v[76:79], v[32:35], v[72:75]
	s_waitcnt lgkmcnt(2)
	v_mfma_f32_16x16x32_bf16 v[72:75], v[90:93], v[36:39], v[72:75]
	s_waitcnt lgkmcnt(1)
	v_mfma_f32_16x16x32_bf16 v[72:75], v[184:187], v[40:43], v[72:75]
	s_waitcnt lgkmcnt(0)
	v_mfma_f32_16x16x32_bf16 v[72:75], v[188:191], v[44:47], v[72:75]
	v_mfma_f32_16x16x32_bf16 v[90:93], v[68:71], v[4:7], 0
	v_mfma_f32_16x16x32_bf16 v[94:97], v[68:71], v[8:11], 0
	s_nop 5
	v_mul_f32_e32 v76, 0x3d122279, v72
	v_fmaak_f32 v76, v72, v76, 0x3f4c422a
	v_mul_f32_e32 v76, v72, v76
	v_mul_f32_e32 v77, 0x3d122279, v73
	v_add_f32_e32 v76, v76, v76
	v_fmaak_f32 v77, v73, v77, 0x3f4c422a
	v_mul_f32_e32 v76, 0xbfb8aa3b, v76
	v_mul_f32_e32 v77, v73, v77
	v_exp_f32_e32 v76, v76
	v_add_f32_e32 v77, v77, v77
	v_mul_f32_e32 v77, 0xbfb8aa3b, v77
	v_exp_f32_e32 v77, v77
	v_add_f32_e32 v76, 1.0, v76
	v_rcp_f32_e32 v76, v76
	v_mfma_f32_16x16x32_bf16 v[98:101], v[68:71], v[12:15], 0
	v_add_f32_e32 v77, 1.0, v77
	v_rcp_f32_e32 v77, v77
	v_mul_f32_e32 v72, v72, v76
	v_cvt_pk_bf16_f32 v72, v72, v72
	ds_write_b16 v160, v72 offset:15616
	v_mul_f32_e32 v72, v73, v77
	v_mul_f32_e32 v73, 0x3d122279, v74
	v_fmaak_f32 v73, v74, v73, 0x3f4c422a
	v_mul_f32_e32 v73, v74, v73
	v_add_f32_e32 v73, v73, v73
	v_mul_f32_e32 v73, 0xbfb8aa3b, v73
	v_exp_f32_e32 v73, v73
	v_mul_f32_e32 v76, 0x3d122279, v75
	v_fmaak_f32 v86, v75, v76, 0x3f4c422a
	v_mul_f32_e32 v86, v75, v86
	v_add_f32_e32 v86, v86, v86
	v_add_f32_e32 v73, 1.0, v73
	v_mul_f32_e32 v86, 0xbfb8aa3b, v86
	v_rcp_f32_e32 v73, v73
	v_exp_f32_e32 v86, v86
	v_cvt_pk_bf16_f32 v72, v72, v72
	ds_write_b16 v160, v72 offset:15648
	v_mul_f32_e32 v72, v74, v73
	v_add_f32_e32 v73, 1.0, v86
	v_rcp_f32_e32 v73, v73
	v_mfma_f32_16x16x32_bf16 v[76:79], v[68:71], v[0:3], 0
	v_cvt_pk_bf16_f32 v72, v72, v72
	ds_write_b16 v160, v72 offset:15680
	v_mul_f32_e32 v72, v75, v73
	v_cvt_pk_bf16_f32 v86, v72, v72
	v_mfma_f32_16x16x32_bf16 v[72:75], v[68:71], v[16:19], 0
	ds_write_b16 v163, v86 offset:14592
	s_nop 0
	s_nop 3
	ds_write_b128 v81, v[76:79]
	v_mfma_f32_16x16x32_bf16 v[76:79], v[68:71], v[20:23], 0
	ds_write_b128 v81, v[90:93] offset:1280
	ds_write_b128 v81, v[94:97] offset:2560
	ds_write_b128 v83, v[98:101]
	v_mfma_f32_16x16x32_bf16 v[90:93], v[68:71], v[24:27], 0
	ds_write_b128 v81, v[72:75] offset:5120
	s_nop 2
	ds_write_b128 v81, v[76:79] offset:6400
	s_nop 2
	ds_write_b128 v81, v[90:93] offset:7680
	v_mul_f32_e32 v81, v132, v111
	v_mfma_f32_16x16x32_bf16 v[72:75], v[68:71], v[28:31], 0
	v_fma_f32 v81, v128, v110, -v81
	v_mfma_f32_16x16x32_bf16 v[68:71], v[68:71], v[48:51], 0
	s_nop 5
	ds_write_b128 v88, v[72:75]
	s_waitcnt lgkmcnt(0)
	ds_read_b128 v[72:75], v82
	ds_read_b128 v[76:79], v82 offset:16
	ds_read_b128 v[86:89], v82 offset:32
	ds_read_b128 v[90:93], v82 offset:48
	ds_read_b128 v[94:97], v82 offset:5120
	ds_read_b128 v[98:101], v82 offset:5136
	ds_read_b128 v[102:105], v82 offset:5152
	ds_read_b128 v[106:109], v82 offset:5168
	s_waitcnt lgkmcnt(7)
	v_add_f32_e32 v72, v81, v72
	v_mul_f32_e32 v81, v128, v111
	v_fmac_f32_e32 v81, v132, v110
	s_waitcnt lgkmcnt(3)
	v_add_f32_e32 v81, v81, v94
	v_cvt_pk_bf16_f32 v82, v72, v81
	ds_write_b32 v149, v82 offset:10240
	v_mul_f32_e32 v82, v132, v81
	v_mul_f32_e32 v81, v128, v81
	v_fma_f32 v82, v128, v72, -v82
	v_fmac_f32_e32 v81, v132, v72
	v_add_f32_e32 v73, v73, v82
	v_add_f32_e32 v72, v95, v81
	v_cvt_pk_bf16_f32 v81, v73, v72
	ds_write_b32 v149, v81 offset:10512
	v_mul_f32_e32 v81, v132, v72
	v_mul_f32_e32 v72, v128, v72
	v_fma_f32 v81, v128, v73, -v81
	v_fmac_f32_e32 v72, v132, v73
	v_add_f32_e32 v74, v74, v81
	v_add_f32_e32 v72, v96, v72
	v_cvt_pk_bf16_f32 v73, v74, v72
	ds_write_b32 v149, v73 offset:10784
	v_mul_f32_e32 v73, v132, v72
	v_mul_f32_e32 v72, v128, v72
	v_fma_f32 v73, v128, v74, -v73
	v_fmac_f32_e32 v72, v132, v74
	v_add_f32_e32 v73, v75, v73
	v_add_f32_e32 v72, v97, v72
	v_cvt_pk_bf16_f32 v74, v73, v72
	ds_write_b32 v149, v74 offset:11056
	v_mul_f32_e32 v74, v132, v72
	v_mul_f32_e32 v72, v128, v72
	v_fma_f32 v74, v128, v73, -v74
	v_fmac_f32_e32 v72, v132, v73
	v_add_f32_e32 v74, v76, v74
	s_waitcnt lgkmcnt(6)
	v_add_f32_e32 v72, v98, v72
	v_cvt_pk_bf16_f32 v73, v74, v72
	ds_write_b32 v149, v73 offset:11328
	v_mul_f32_e32 v73, v132, v72
	v_mul_f32_e32 v72, v128, v72
	v_fma_f32 v73, v128, v74, -v73
	v_fmac_f32_e32 v72, v132, v74
	v_add_f32_e32 v73, v77, v73
	v_add_f32_e32 v72, v99, v72
	v_cvt_pk_bf16_f32 v74, v73, v72
	ds_write_b32 v149, v74 offset:11600
	v_mul_f32_e32 v74, v132, v72
	v_mul_f32_e32 v72, v128, v72
	v_fma_f32 v74, v128, v73, -v74
	v_fmac_f32_e32 v72, v132, v73
	v_add_f32_e32 v74, v78, v74
	v_add_f32_e32 v72, v100, v72
	v_cvt_pk_bf16_f32 v73, v74, v72
	ds_write_b32 v149, v73 offset:11872
	v_mul_f32_e32 v73, v132, v72
	v_mul_f32_e32 v72, v128, v72
	v_fma_f32 v73, v128, v74, -v73
	v_fmac_f32_e32 v72, v132, v74
	v_add_f32_e32 v73, v79, v73
	v_add_f32_e32 v72, v101, v72
	v_cvt_pk_bf16_f32 v74, v73, v72
	ds_write_b32 v149, v74 offset:12144
	v_mul_f32_e32 v74, v132, v72
	v_mul_f32_e32 v72, v128, v72
	v_fma_f32 v74, v128, v73, -v74
	v_fmac_f32_e32 v72, v132, v73
	v_add_f32_e32 v74, v86, v74
	s_waitcnt lgkmcnt(9)
	v_add_f32_e32 v72, v102, v72
	v_cvt_pk_bf16_f32 v73, v74, v72
	ds_write_b32 v149, v73 offset:12416
	v_mul_f32_e32 v73, v132, v72
	v_mul_f32_e32 v72, v128, v72
	v_fma_f32 v73, v128, v74, -v73
	v_fmac_f32_e32 v72, v132, v74
	v_add_f32_e32 v73, v87, v73
	v_add_f32_e32 v72, v103, v72
	v_cvt_pk_bf16_f32 v74, v73, v72
	ds_write_b32 v149, v74 offset:12688
	v_mul_f32_e32 v74, v132, v72
	v_mul_f32_e32 v72, v128, v72
	v_fma_f32 v74, v128, v73, -v74
	v_fmac_f32_e32 v72, v132, v73
	v_add_f32_e32 v74, v88, v74
	v_add_f32_e32 v72, v104, v72
	v_cvt_pk_bf16_f32 v73, v74, v72
	ds_write_b32 v149, v73 offset:12960
	v_mul_f32_e32 v73, v132, v72
	v_mul_f32_e32 v72, v128, v72
	v_fma_f32 v73, v128, v74, -v73
	v_fmac_f32_e32 v72, v132, v74
	v_add_f32_e32 v75, v89, v73
	v_add_f32_e32 v73, v105, v72
	v_cvt_pk_bf16_f32 v72, v75, v73
	ds_write_b32 v149, v72 offset:13232
	v_mul_f32_e32 v72, v132, v73
	v_mul_f32_e32 v73, v128, v73
	v_fma_f32 v72, v128, v75, -v72
	v_fmac_f32_e32 v73, v132, v75
	v_mov_b32_e32 v74, v90
	s_waitcnt lgkmcnt(12)
	v_mov_b32_e32 v75, v106
	v_pk_add_f32 v[72:73], v[74:75], v[72:73]
	v_mov_b32_e32 v106, v91
	v_cvt_pk_bf16_f32 v74, v72, v73
	ds_write_b32 v149, v74 offset:13504
	v_pk_mul_f32 v[74:75], v[132:133], v[72:73]
	s_nop 0
	v_pk_fma_f32 v[76:77], v[128:129], v[72:73], v[74:75] op_sel:[0,0,1] op_sel_hi:[1,1,0] neg_lo:[0,0,1] neg_hi:[0,0,1]
	v_pk_fma_f32 v[72:73], v[128:129], v[72:73], v[74:75] op_sel:[0,0,1] op_sel_hi:[1,1,0]
	s_nop 0
	v_mov_b32_e32 v77, v73
	v_pk_add_f32 v[72:73], v[106:107], v[76:77]
	s_nop 0
	v_cvt_pk_bf16_f32 v74, v72, v73
	ds_write_b32 v149, v74 offset:13776
	v_pk_mul_f32 v[74:75], v[132:133], v[72:73]
	s_nop 0
	v_pk_fma_f32 v[76:77], v[128:129], v[72:73], v[74:75] op_sel:[0,0,1] op_sel_hi:[1,1,0] neg_lo:[0,0,1] neg_hi:[0,0,1]
	v_pk_fma_f32 v[72:73], v[128:129], v[72:73], v[74:75] op_sel:[0,0,1] op_sel_hi:[1,1,0]
	s_nop 0
	v_mov_b32_e32 v77, v73
	v_mov_b32_e32 v72, v92
	v_mov_b32_e32 v73, v108
	v_pk_add_f32 v[72:73], v[72:73], v[76:77]
	v_mov_b32_e32 v108, v93
	v_cvt_pk_bf16_f32 v74, v72, v73
	ds_write_b32 v149, v74 offset:14048
	v_pk_mul_f32 v[74:75], v[132:133], v[72:73]
	s_nop 0
	v_pk_fma_f32 v[76:77], v[128:129], v[72:73], v[74:75] op_sel:[0,0,1] op_sel_hi:[1,1,0] neg_lo:[0,0,1] neg_hi:[0,0,1]
	v_pk_fma_f32 v[72:73], v[128:129], v[72:73], v[74:75] op_sel:[0,0,1] op_sel_hi:[1,1,0]
	s_nop 0
	v_mov_b32_e32 v77, v73
	v_pk_add_f32 v[86:87], v[108:109], v[76:77]
	s_nop 0
	v_cvt_pk_bf16_f32 v72, v86, v87
	ds_write_b32 v149, v72 offset:14320
	s_waitcnt lgkmcnt(0)
	ds_read_b128 v[72:75], v80 offset:10240
	ds_read_b128 v[76:79], v80 offset:10304
	ds_read_b128 v[184:187], v80 offset:10368
	ds_read_b128 v[188:191], v80 offset:10432
	s_waitcnt lgkmcnt(3)
	v_mfma_f32_16x16x32_bf16 v[68:71], v[72:75], v[32:35], v[68:71]
	s_waitcnt lgkmcnt(2)
	v_mfma_f32_16x16x32_bf16 v[68:71], v[76:79], v[36:39], v[68:71]
	s_waitcnt vmcnt(3)
	v_mov_b64_e32 v[82:83], v[54:55]
	v_mov_b64_e32 v[80:81], v[52:53]
	s_waitcnt lgkmcnt(1)
	v_mfma_f32_16x16x32_bf16 v[68:71], v[184:187], v[40:43], v[68:71]
	s_waitcnt lgkmcnt(0)
	v_mfma_f32_16x16x32_bf16 v[68:71], v[188:191], v[44:47], v[68:71]
	s_waitcnt vmcnt(2)
	v_mov_b64_e32 v[78:79], v[58:59]
	v_mov_b64_e32 v[76:77], v[56:57]
	s_nop 4
	v_mul_f32_e32 v72, 0x3d122279, v68
	v_fmaak_f32 v72, v68, v72, 0x3f4c422a
	v_mul_f32_e32 v72, v68, v72
	v_mul_f32_e32 v73, 0x3d122279, v69
	v_add_f32_e32 v72, v72, v72
	v_fmaak_f32 v73, v69, v73, 0x3f4c422a
	v_mul_f32_e32 v72, 0xbfb8aa3b, v72
	v_mul_f32_e32 v73, v69, v73
	v_exp_f32_e32 v72, v72
	v_add_f32_e32 v73, v73, v73
	v_mul_f32_e32 v73, 0xbfb8aa3b, v73
	v_exp_f32_e32 v73, v73
	v_add_f32_e32 v72, 1.0, v72
	v_rcp_f32_e32 v72, v72
	v_add_f32_e32 v73, 1.0, v73
	v_rcp_f32_e32 v73, v73
	v_mul_f32_e32 v68, v68, v72
	v_cvt_pk_bf16_f32 v68, v68, v68
	ds_write_b16 v160, v68 offset:16128
	v_mul_f32_e32 v68, v69, v73
	v_mul_f32_e32 v69, 0x3d122279, v70
	v_mul_f32_e32 v72, 0x3d122279, v71
	v_fmaak_f32 v69, v70, v69, 0x3f4c422a
	v_fmaak_f32 v72, v71, v72, 0x3f4c422a
	v_mul_f32_e32 v69, v70, v69
	v_mul_f32_e32 v72, v71, v72
	v_add_f32_e32 v69, v69, v69
	v_add_f32_e32 v72, v72, v72
	v_mul_f32_e32 v69, 0xbfb8aa3b, v69
	v_mul_f32_e32 v72, 0xbfb8aa3b, v72
	v_exp_f32_e32 v69, v69
	v_exp_f32_e32 v72, v72
	v_cvt_pk_bf16_f32 v68, v68, v68
	ds_write_b16 v160, v68 offset:16160
	v_add_f32_e32 v69, 1.0, v69
	v_add_f32_e32 v68, 1.0, v72
	v_rcp_f32_e32 v69, v69
	v_rcp_f32_e32 v68, v68
	s_waitcnt vmcnt(1)
	v_mov_b64_e32 v[74:75], v[62:63]
	v_mov_b64_e32 v[72:73], v[60:61]
	v_mul_f32_e32 v69, v70, v69
	v_mul_f32_e32 v68, v71, v68
	v_cvt_pk_bf16_f32 v69, v69, v69
	ds_write_b16 v160, v69 offset:16192
	v_cvt_pk_bf16_f32 v68, v68, v68
	ds_write_b16 v164, v68 offset:14592
	s_waitcnt lgkmcnt(0)
	s_waitcnt vmcnt(0)
	v_mov_b64_e32 v[70:71], v[66:67]
	v_mov_b64_e32 v[68:69], v[64:65]
